# grid barrier poll loop without the sleep between polls
# speedup vs baseline: 1.0003x; 1.0003x over previous
; __global__ void __launch_bounds__(512) mega(Params P) {
;     ...
;   grid.sync();
.Lgbx_poll_0:
	global_load_dword v3, v1, s[4:5] sc1
	s_waitcnt vmcnt(0)
	v_and_b32_e32 v3, 0xffff0000, v3
	v_cmp_ne_u32_e32 vcc, v3, v0
	s_cbranch_vccnz .Lgbx_sw_0
	s_branch .Lgbx_poll_0

; __global__ void __launch_bounds__(512) mega(Params P) {
;     ...
;   for (int l = 0; l < 2; ++l) {
;     if (l > 0) { norm_phase(H, P.attn_norm + l * DM, HN); grid.sync(); }
;     { EpiIn e; e.cqkv = CQKV; e.ka = (bf16_t*)(ws + WS_KA); e.qd = (bf16_t*)(ws + WS_QD); e.kd = (bf16_t*)(ws + WS_KD); e.vtd = (bf16_t*)(ws + WS_VTD);
;       e.qs = (bf16_t*)(ws + WS_QS); e.ks = (bf16_t*)(ws + WS_KS); e.vts = (bf16_t*)(ws + WS_VTS); e.rope = rope;
;       if (EN & 2) gemm_phase(HN, DM, (const bf16_t*)(ws + WS_WIN) + (size_t)l * N_IN * 1024, 1024, NREAL, N_IN, 1024, e); }
;     grid.sync();
;     { EpiUp e; e.qa = (bf16_t*)(ws + WS_QA); e.ka = (bf16_t*)(ws + WS_KA); e.vta = (bf16_t*)(ws + WS_VTA); e.rope = rope; e.brow = 0; e.rs_direct = 0.f; e.use_direct = 0;
;       if (EN & 4) up_phase(CQKV, (const bf16_t*)(ws + WS_WQB) + (size_t)l * 768 * 256, (const bf16_t*)(ws + WS_WKVB) + (size_t)l * 768 * 256, e); }
;     grid.sync();
;     attn_phase(P, l);
;     grid.sync();
;     if (l == 0) { EpiResid0 e; e.H = H; e.xsrc = P.x; e.msrc = P.meta; gemm_phase(HN, DM, (const bf16_t*)(ws + WS_WOUT), 1024, NREAL, 1024, 1024, e); }
;     else { EpiResid e; e.H = H; gemm_phase(HN, DM, (const bf16_t*)(ws + WS_WOUT) + (size_t)l * 1024 * 1024, 1024, NREAL, 1024, 1024, e); }
;     grid.sync();
;     norm_phase(H, P.ffn_norm + l * DM, HN);
;     grid.sync();
;     if (EN & 128) { EpiGU e; e.act = (bf16_t*)(ws + WS_ACT); gemm_phase(HN, DM, (const bf16_t*)(ws + WS_WGU) + (size_t)l * N_GU * 1024, 1024, NREAL, N_GU, 1024, e); }
;     grid.sync();
;     if (EN & 256) { EpiResid e; e.H = H; gemm_phase((const bf16_t*)(ws + WS_ACT), DFF, (const bf16_t*)(ws + WS_WDN) + (size_t)l * 1024 * DFF, DFF, NREAL, 1024, DFF, e); }
;     grid.sync();
.Lgbx_poll_4:
	global_load_dword v3, v1, s[6:7] sc1
	s_waitcnt vmcnt(0)
	v_and_b32_e32 v3, 0xffff0000, v3
	v_cmp_ne_u32_e32 vcc, v3, v0
	s_cbranch_vccnz .Lgbx_sw_4
	s_branch .Lgbx_poll_4
